# MLA staggered stream: static s_setprio 1 for waves 4-7 inside the MLA loop
# baseline (speedup 1.0000x reference)
.Lmla_stag_entry:
	s_setprio 1
	global_load_dwordx4 v[158:161], v176, s[18:19]
	global_load_dwordx4 v[162:165], v178, s[16:17]
	s_nop 1
	v_add_u32_e32 v176, 0x2000, v176
	v_add_u32_e32 v178, 0x20000, v178

; __device__ __forceinline__ void attn_unit7(const unsigned char* __restrict__ Q8, int ldq, const unsigned char* __restrict__ Kn8, int ldk, const unsigned char* __restrict__ Kr8, ...
;     ...
;   qkt9(pB0, pB1, Kn_lds + 8192, Kr_lds + 4096, qf, 7.0f - m_reg, r32, hi);
;   finishSM9(pA0, pA1, alA, l_reg, p8);
.Lmla_q1_cont:
	v_mov_b32_e32 v0, v218
	s_setprio 0
	s_branch .LBB0_1343
